# grid barrier leader tail: release the XCD (generation bump) before the leader's own L1 invalidate instead of after
# speedup vs baseline: 1.0084x; 1.0084x over previous
; DEVI unsigned xb_ld(unsigned* p)              { return __hip_atomic_load(p, __ATOMIC_RELAXED, __HIP_MEMORY_SCOPE_AGENT); }
; DEVI unsigned xb_add(unsigned* p, unsigned v) { return __hip_atomic_fetch_add(p, v, __ATOMIC_RELAXED, __HIP_MEMORY_SCOPE_AGENT); }
; #define XB_SPIN(cond, bar) do { unsigned _sp = 0; while (cond) { __builtin_amdgcn_s_sleep(1); \
;     if ((++_sp & 255u) == 0u) { if (xb_ld(&(bar)[XB_TMO])) break; if (_sp > XB_SPIN_CAP) { atomicAdd(&(bar)[XB_TMO], 1u); break; } } } } while (0)
; DEVI void xcd_barrier(const XcdBarrier& b) {
;     ...
;         const unsigned old = xb_add(&bar[XB_XSUB(b.x)], 1u);
;         const unsigned gen = old / nloc;
;         if (old + 1u == (gen + 1u) * nloc) {
;             __builtin_amdgcn_fence(__ATOMIC_RELEASE, "agent");
;             asm volatile("s_waitcnt vmcnt(0)" ::: "memory");
;             const unsigned og = xb_add(&bar[XB_TOP], 1u);
;             const unsigned tg = og / nx;
;             if (og + 1u == (tg + 1u) * nx) xb_add(&bar[XB_TOPGEN], 1u);
;             else XB_SPIN(xb_ld(&bar[XB_TOPGEN]) == tg, bar);
;             __builtin_amdgcn_fence(__ATOMIC_ACQUIRE, "agent");
;             xb_add(&bar[XB_XGEN(b.x)], 1u);
;             asm volatile("s_waitcnt vmcnt(0)" ::: "memory");
.LBB0_262:
	s_or_b64 exec, exec, s[4:5]
	global_atomic_add v[158:159], v161, off
	buffer_inv sc1
	s_waitcnt vmcnt(0)
